# v10 + attention bias-table build reads rel_bias from a 3KB LDS copy (ds_read instead of serialized global loads)
# speedup vs baseline: 1.0131x; 1.0031x over previous
.LBB0_658:
	v_mov_b32_e32 v1, v0
	v_readlane_b32 s0, v252, 8
	v_mbcnt_lo_u32_b32 v1, -1, v1
	v_mbcnt_hi_u32_b32 v1, -1, v1
	v_add_u32_e32 v2, s0, v1
	s_mov_b64 s[4:5], s[56:57]
	s_movk_i32 s0, 0x2a48
	s_nop 0
	v_cmp_gt_i32_e32 vcc, s0, v2
	s_mov_b64 s[0:1], exec
	v_readlane_b32 s68, v255, 11
	v_readlane_b32 s38, v255, 8
	v_readlane_b32 s69, v255, 12
	v_readlane_b32 s39, v255, 9
	v_readlane_b32 s36, v255, 31
	s_and_b64 s[6:7], s[0:1], vcc
	v_readlane_b32 s70, v255, 17
	v_readlane_b32 s54, v255, 23
	v_readlane_b32 s55, v255, 24
	v_readlane_b32 s37, v255, 32
	v_readlane_b32 s58, v255, 25
	v_readlane_b32 s60, v255, 26
	s_movk_i32 s61, 0x1a00
	s_movk_i32 s34, 0xc0
	s_mov_b32 s62, 0xc0000
	s_movk_i32 s63, 0x1000
	s_mov_b32 s16, 0x48a8048b
	s_movk_i32 s17, 0xfe3d
	s_movk_i32 s18, 0x60
	s_movk_i32 s19, 0x1c30
	s_movk_i32 s20, 0xfeff
	s_mov_b32 s39, 0xff800000
	s_movk_i32 s21, 0x710
	s_mov_b32 s64, 0xc2ce8ed0
	s_mov_b32 s65, 0x42b17218
	v_readlane_b32 s66, v255, 27
	s_movk_i32 s40, 0x70
	s_movk_i32 s41, 0x140
	s_mov_b32 s42, 0x6a701000
	s_mov_b32 s43, 0x6a700000
	s_mov_b32 s67, 0x40000
	s_mov_b32 s44, 0x80000
	v_readlane_b32 s69, v255, 28
	v_readlane_b32 s71, v255, 30
	s_load_dwordx2 s[100:101], s[56:57], 0x10
	v_lshlrev_b32_e32 v8, 4, v2
	v_add_u32_e32 v9, 0x1a980, v8
	v_cmp_gt_u32_e32 vcc, 0xc0, v2
	s_and_saveexec_b64 s[12:13], vcc
	s_waitcnt lgkmcnt(0)
	global_load_dwordx4 v[4:7], v8, s[100:101]
	s_waitcnt vmcnt(0)
	ds_write_b128 v9, v[4:7]
	s_or_b64 exec, exec, s[12:13]
	s_waitcnt lgkmcnt(0)
	s_barrier
	s_mov_b32 s100, 0x1a980
	s_mov_b64 exec, s[6:7]
	s_cbranch_execz .LBB0_666
	s_load_dwordx2 s[10:11], s[4:5], 0x10
	v_max_i32_e32 v1, 0x2848, v2
	v_sub_u32_e32 v1, v1, v2
	v_add_u32_e32 v1, 0x1ff, v1
	s_movk_i32 s3, 0x1ff
	v_cmp_lt_u32_e32 vcc, s3, v1
	s_mov_b64 s[4:5], -1
	v_mov_b32_e32 v3, v2
	s_and_saveexec_b64 s[12:13], vcc
	s_cbranch_execz .LBB0_663
	v_lshrrev_b32_e32 v1, 9, v1
	v_add_u32_e32 v1, 1, v1
	v_and_b32_e32 v8, 0xfffffe, v1
	v_add_u32_e32 v3, 0x200, v2
	s_mov_b64 s[14:15], 0
	v_mov_b32_e32 v9, v8
	v_mov_b64_e32 v[4:5], v[2:3]
	s_mov_b32 s22, 0x3fb8aa3b
.LBB0_661:
	v_mul_hi_i32 v3, v4, s16
	v_lshrrev_b32_e32 v6, 31, v3
	v_ashrrev_i32_e32 v3, 7, v3
	v_add_u32_e32 v10, v3, v6
	v_mul_hi_i32 v3, v5, s16
	v_lshrrev_b32_e32 v6, 31, v3
	v_ashrrev_i32_e32 v3, 7, v3
	v_add_u32_e32 v12, v3, v6
	v_mov_b32_e32 v14, v5
	v_mad_u64_u32 v[14:15], s[4:5], v12, s17, v[14:15]
	v_mad_u64_u32 v[6:7], s[4:5], v10, s17, v[4:5]
	v_min_i32_e32 v3, 0x161, v14
	v_min_i32_e32 v7, 0x161, v6
	v_add_u32_e32 v3, 0xffffff1f, v3
	v_cmp_lt_i32_e32 vcc, s18, v14
	v_add_u32_e32 v7, 0xffffff1f, v7
	v_add_u32_e32 v9, -2, v9
	v_cndmask_b32_e32 v3, v203, v3, vcc
	v_cmp_lt_i32_e32 vcc, s18, v6
	v_mul_lo_u32 v16, v3, v3
	v_ffbh_u32_e32 v16, v16
	v_cndmask_b32_e32 v7, v203, v7, vcc
	v_mul_lo_u32 v15, v7, v7
	v_ffbh_u32_e32 v15, v15
	v_sub_u32_e32 v11, 0, v7
	v_min_u32_e32 v15, 32, v15
	v_max_i32_e32 v11, v7, v11
	v_sub_u32_e32 v13, 0, v3
	v_min_u32_e32 v16, 32, v16
	v_sub_u32_e32 v15, 33, v15
	v_cmp_lt_i32_e64 s[4:5], 0, v7
	v_max_i32_e32 v13, v3, v13
	v_sub_u32_e32 v16, 33, v16
	v_min_u32_e32 v15, 15, v15
	v_cmp_lt_i32_e32 vcc, 0, v3
	v_cndmask_b32_e64 v3, 0, 16, s[4:5]
	v_cmp_gt_u32_e64 s[4:5], 8, v11
	v_min_u32_e32 v16, 15, v16
	v_cndmask_b32_e64 v7, 0, 16, vcc
	v_cmp_gt_u32_e32 vcc, 8, v13
	v_cndmask_b32_e64 v11, v15, v11, s[4:5]
	v_add_u32_e32 v3, v11, v3
	v_cndmask_b32_e32 v13, v16, v13, vcc
	v_add_u32_e32 v7, v13, v7
	v_mad_u64_u32 v[16:17], s[4:5], v3, 24, v[10:11]
	v_mad_u64_u32 v[18:19], s[4:5], v7, 24, v[12:13]
	v_ashrrev_i32_e32 v17, 31, v16
	v_ashrrev_i32_e32 v19, 31, v18
	s_waitcnt lgkmcnt(0)
	v_lshl_add_u32 v16, v16, 2, s100
	v_lshl_add_u32 v18, v18, 2, s100
	ds_read_b32 v16, v16
	s_nop 0
	ds_read_b32 v17, v18
	v_add_u32_e32 v7, 0xfffffe9e, v14
	v_cmp_gt_i32_e32 vcc, s19, v5
	v_add_u32_e32 v3, 0xfffffe9e, v6
	v_cmp_gt_u32_e64 s[6:7], s20, v7
	v_cmp_gt_i32_e64 s[4:5], s19, v4
	v_cmp_gt_u32_e64 s[8:9], s20, v3
	s_and_b64 vcc, vcc, s[6:7]
	s_and_b64 s[4:5], s[4:5], s[8:9]
	v_mul_lo_u32 v10, v10, s21
	s_add_i32 s3, 0, 0x10000
	v_lshlrev_b32_e32 v6, 2, v6
	v_mul_lo_u32 v11, v12, s21
	v_add3_u32 v6, s3, v10, v6
	v_lshlrev_b32_e32 v10, 2, v14
	v_add_u32_e32 v5, 0x400, v5
	v_add_u32_e32 v4, 0x400, v4
	v_add3_u32 v10, s3, v11, v10
	s_waitcnt lgkmcnt(0)
	v_pk_mul_f32 v[16:17], v[16:17], s[22:23] op_sel_hi:[1,0]
	s_nop 0
	v_cndmask_b32_e32 v3, v17, v218, vcc
	v_cmp_eq_u32_e32 vcc, 0, v9
	v_cndmask_b32_e64 v7, v16, v218, s[4:5]
	s_or_b64 s[14:15], vcc, s[14:15]
	ds_write_b32 v6, v7
	ds_write_b32 v10, v3
	s_andn2_b64 exec, exec, s[14:15]
	s_cbranch_execnz .LBB0_661
	s_or_b64 exec, exec, s[14:15]
	v_cmp_ne_u32_e32 vcc, v1, v8
	v_lshl_add_u32 v3, v8, 9, v2
	s_orn2_b64 s[4:5], vcc, exec

.LBB0_665:
	v_mul_hi_i32 v1, v3, s16
	v_lshrrev_b32_e32 v4, 31, v1
	v_ashrrev_i32_e32 v1, 7, v1
	v_add_u32_e32 v4, v1, v4
	v_mad_i32_i24 v1, v4, s17, v3
	v_min_i32_e32 v5, 0x161, v1
	v_add_u32_e32 v5, 0xffffff1f, v5
	v_cmp_lt_i32_e32 vcc, s18, v1
	s_add_i32 s3, 0, 0x10000
	s_nop 0
	v_cndmask_b32_e32 v5, v203, v5, vcc
	v_mul_lo_u32 v7, v5, v5
	v_ffbh_u32_e32 v7, v7
	v_sub_u32_e32 v6, 0, v5
	v_min_u32_e32 v7, 32, v7
	v_max_i32_e32 v6, v5, v6
	v_sub_u32_e32 v7, 33, v7
	v_cmp_lt_i32_e32 vcc, 0, v5
	v_min_u32_e32 v7, 15, v7
	s_nop 0
	v_cndmask_b32_e64 v5, 0, 16, vcc
	v_cmp_gt_u32_e32 vcc, 8, v6
	s_nop 1
	v_cndmask_b32_e32 v6, v7, v6, vcc
	v_add_u32_e32 v5, v6, v5
	v_mad_u64_u32 v[6:7], s[4:5], v5, 24, v[4:5]
	v_ashrrev_i32_e32 v7, 31, v6
	s_waitcnt lgkmcnt(0)
	v_lshl_add_u32 v6, v6, 2, s100
	ds_read_b32 v5, v6
	v_add_u32_e32 v6, 0xfffffe9e, v1
	v_cmp_gt_i32_e32 vcc, s19, v3
	v_cmp_gt_u32_e64 s[4:5], s20, v6
	s_and_b64 vcc, vcc, s[4:5]
	v_mul_i32_i24_e32 v4, 0x710, v4
	v_lshlrev_b32_e32 v1, 2, v1
	v_add3_u32 v1, s3, v4, v1
	s_movk_i32 s3, 0x2847
	s_waitcnt lgkmcnt(0)
	v_mul_f32_e32 v5, 0x3fb8aa3b, v5
	v_cndmask_b32_e32 v5, v5, v218, vcc
	ds_write_b32 v1, v5
	v_add_u32_e32 v1, 0x200, v3
	v_cmp_lt_i32_e32 vcc, s3, v3
	s_or_b64 s[6:7], vcc, s[6:7]
	v_mov_b32_e32 v3, v1
	s_andn2_b64 exec, exec, s[6:7]
	s_cbranch_execnz .LBB0_665
